# layer-1 norm row loop: all four row loads issued together (compiler had 2 loads, wait, 2 loads)
# speedup vs baseline: 1.1724x; 1.0001x over previous
.LBB0_858:
	s_movk_i32 s6, 0x4000
	v_cmp_gt_i32_e32 vcc, s6, v16
	v_add_u32_e32 v34, 0xffffc000, v16
	v_ashrrev_i32_e32 v17, 31, v16
	v_cndmask_b32_e32 v35, 0, v17, vcc
	v_cndmask_b32_e32 v34, v34, v16, vcc
	v_cndmask_b32_e32 v37, v14, v15, vcc
	v_cndmask_b32_e32 v36, v31, v32, vcc
	v_lshlrev_b64 v[34:35], 12, v[34:35]
	v_lshl_add_u64 v[34:35], v[36:37], 0, v[34:35]
	v_lshl_add_u64 v[42:43], v[34:35], 0, v[18:19]
	v_and_b32_e32 v34, -2, v16
	v_mov_b32_e32 v35, v17
	v_lshlrev_b64 v[34:35], 11, v[34:35]
	v_and_b32_e32 v200, 1, v16
	v_lshl_or_b32 v34, v200, 6, v34
	v_lshl_add_u64 v[44:45], v[20:21], 0, v[34:35]
	global_load_dwordx4 v[34:37], v[42:43], off
	global_load_dwordx4 v[38:41], v[42:43], off offset:1024
	global_load_dwordx4 v[72:75], v[42:43], off offset:2048
	global_load_dwordx4 v[76:79], v[42:43], off offset:3072
	s_mov_b32 s6, 0x800000
	v_add_u32_e32 v16, s4, v16
	s_waitcnt vmcnt(3)
	v_mov_b32_e32 v46, v34
	s_waitcnt vmcnt(2)
	v_mov_b32_e32 v50, v38
	v_mov_b32_e32 v55, v38
	v_mov_b32_e32 v38, v35
	v_mov_b32_e32 v48, v35
	v_mov_b32_e32 v54, v34
	v_pk_mul_f32 v[34:35], v[38:39], v[38:39]
	v_mov_b32_e32 v52, v39
	v_pk_fma_f32 v[34:35], v[54:55], v[54:55], v[34:35]
	v_mov_b32_e32 v38, v36
	v_mov_b32_e32 v39, v40
	v_mov_b32_e32 v51, v40
	v_pk_fma_f32 v[34:35], v[38:39], v[38:39], v[34:35]
	v_mov_b32_e32 v40, v37
	v_mov_b32_e32 v47, v36
	v_mov_b32_e32 v49, v37
	v_mov_b32_e32 v53, v41
	v_pk_fma_f32 v[54:55], v[40:41], v[40:41], v[34:35]
	v_add_f32_e32 v17, v54, v55
	s_waitcnt vmcnt(1)
	v_mov_b32_e32 v56, v72
	s_waitcnt vmcnt(0)
	v_mov_b32_e32 v42, v76
	v_mov_b32_e32 v63, v76
	v_mov_b32_e32 v76, v73
	v_mov_b32_e32 v58, v73
	v_mov_b32_e32 v62, v72
	v_pk_mul_f32 v[72:73], v[76:77], v[76:77]
	v_mov_b32_e32 v60, v77
	v_pk_fma_f32 v[72:73], v[62:63], v[62:63], v[72:73]
	v_mov_b32_e32 v76, v74
	v_mov_b32_e32 v77, v78
	v_mov_b32_e32 v43, v78
	v_pk_fma_f32 v[72:73], v[76:77], v[76:77], v[72:73]
	v_mov_b32_e32 v78, v75
	v_pk_fma_f32 v[72:73], v[78:79], v[78:79], v[72:73]
	v_mov_b32_e32 v57, v74
	v_add_f32_e32 v17, v17, v72
	v_add_f32_e32 v17, v17, v73
	ds_bpermute_b32 v72, v25, v17
	v_mov_b32_e32 v59, v75
	v_mov_b32_e32 v61, v79
	s_waitcnt lgkmcnt(0)
	v_add_f32_e32 v17, v17, v72
	ds_bpermute_b32 v72, v26, v17
	s_waitcnt lgkmcnt(0)
	v_add_f32_e32 v17, v17, v72
	ds_bpermute_b32 v72, v27, v17
	s_waitcnt lgkmcnt(0)
	v_add_f32_e32 v17, v17, v72
	ds_bpermute_b32 v72, v28, v17
	s_waitcnt lgkmcnt(0)
	v_add_f32_e32 v17, v17, v72
	ds_bpermute_b32 v72, v29, v17
	s_waitcnt lgkmcnt(0)
	v_add_f32_e32 v17, v17, v72
	ds_bpermute_b32 v72, v30, v17
	s_waitcnt lgkmcnt(0)
	v_add_f32_e32 v17, v17, v72
	v_fmamk_f32 v17, v17, 0x3a800000, v24
	v_cmp_gt_f32_e32 vcc, s6, v17
	v_mul_f32_e32 v72, 0x4b800000, v17
	s_movk_i32 s6, 0x407f
	v_cndmask_b32_e32 v17, v17, v72, vcc
	v_rsq_f32_e32 v17, v17
	s_nop 0
	v_mul_f32_e32 v72, 0x45800000, v17
	v_cndmask_b32_e32 v72, v17, v72, vcc
	v_pk_mul_f32 v[74:75], v[46:47], v[72:73] op_sel_hi:[1,0]
	v_pk_mul_f32 v[76:77], v[48:49], v[72:73] op_sel_hi:[1,0]
	v_pk_mul_f32 v[74:75], v[0:1], v[74:75]
	v_pk_mul_f32 v[76:77], v[22:23], v[76:77]
	v_and_b32_sdwa v17, v75, v33 dst_sel:DWORD dst_unused:UNUSED_PAD src0_sel:WORD_1 src1_sel:DWORD
	v_and_b32_sdwa v73, v74, v33 dst_sel:DWORD dst_unused:UNUSED_PAD src0_sel:WORD_1 src1_sel:DWORD
	v_add3_u32 v73, v74, v73, s5
	v_add3_u32 v17, v75, v17, s5
	v_and_b32_sdwa v74, v77, v33 dst_sel:DWORD dst_unused:UNUSED_PAD src0_sel:WORD_1 src1_sel:DWORD
	v_and_b32_sdwa v75, v76, v33 dst_sel:DWORD dst_unused:UNUSED_PAD src0_sel:WORD_1 src1_sel:DWORD
	v_add3_u32 v74, v77, v74, s5
	v_add3_u32 v75, v76, v75, s5
	v_and_b32_e32 v74, 0xffff0000, v74
	v_and_b32_e32 v76, 0xffff0000, v75
	v_or_b32_sdwa v75, v74, v17 dst_sel:DWORD dst_unused:UNUSED_PAD src0_sel:DWORD src1_sel:WORD_1
	v_or_b32_sdwa v74, v76, v73 dst_sel:DWORD dst_unused:UNUSED_PAD src0_sel:DWORD src1_sel:WORD_1
	global_store_dwordx2 v[44:45], v[74:75], off
	v_pk_mul_f32 v[74:75], v[50:51], v[72:73] op_sel_hi:[1,0]
	v_pk_mul_f32 v[76:77], v[52:53], v[72:73] op_sel_hi:[1,0]
	v_pk_mul_f32 v[74:75], v[4:5], v[74:75]
	v_pk_mul_f32 v[76:77], v[2:3], v[76:77]
	v_and_b32_sdwa v17, v75, v33 dst_sel:DWORD dst_unused:UNUSED_PAD src0_sel:WORD_1 src1_sel:DWORD
	v_and_b32_sdwa v73, v74, v33 dst_sel:DWORD dst_unused:UNUSED_PAD src0_sel:WORD_1 src1_sel:DWORD
	v_add3_u32 v73, v74, v73, s5
	v_add3_u32 v17, v75, v17, s5
	v_and_b32_sdwa v74, v77, v33 dst_sel:DWORD dst_unused:UNUSED_PAD src0_sel:WORD_1 src1_sel:DWORD
	v_and_b32_sdwa v75, v76, v33 dst_sel:DWORD dst_unused:UNUSED_PAD src0_sel:WORD_1 src1_sel:DWORD
	v_add3_u32 v74, v77, v74, s5
	v_add3_u32 v75, v76, v75, s5
	v_and_b32_e32 v74, 0xffff0000, v74
	v_and_b32_e32 v76, 0xffff0000, v75
	v_or_b32_sdwa v75, v74, v17 dst_sel:DWORD dst_unused:UNUSED_PAD src0_sel:DWORD src1_sel:WORD_1
	v_or_b32_sdwa v74, v76, v73 dst_sel:DWORD dst_unused:UNUSED_PAD src0_sel:DWORD src1_sel:WORD_1
	global_store_dwordx2 v[44:45], v[74:75], off offset:1024
	v_pk_mul_f32 v[74:75], v[56:57], v[72:73] op_sel_hi:[1,0]
	v_pk_mul_f32 v[76:77], v[58:59], v[72:73] op_sel_hi:[1,0]
	v_pk_mul_f32 v[74:75], v[8:9], v[74:75]
	v_pk_mul_f32 v[76:77], v[6:7], v[76:77]
	v_and_b32_sdwa v17, v75, v33 dst_sel:DWORD dst_unused:UNUSED_PAD src0_sel:WORD_1 src1_sel:DWORD
	v_and_b32_sdwa v73, v74, v33 dst_sel:DWORD dst_unused:UNUSED_PAD src0_sel:WORD_1 src1_sel:DWORD
	v_add3_u32 v73, v74, v73, s5
	v_add3_u32 v17, v75, v17, s5
	v_and_b32_sdwa v74, v77, v33 dst_sel:DWORD dst_unused:UNUSED_PAD src0_sel:WORD_1 src1_sel:DWORD
	v_and_b32_sdwa v75, v76, v33 dst_sel:DWORD dst_unused:UNUSED_PAD src0_sel:WORD_1 src1_sel:DWORD
	v_add3_u32 v74, v77, v74, s5
	v_add3_u32 v75, v76, v75, s5
	v_and_b32_e32 v74, 0xffff0000, v74
	v_and_b32_e32 v76, 0xffff0000, v75
	v_or_b32_sdwa v75, v74, v17 dst_sel:DWORD dst_unused:UNUSED_PAD src0_sel:DWORD src1_sel:WORD_1
	v_or_b32_sdwa v74, v76, v73 dst_sel:DWORD dst_unused:UNUSED_PAD src0_sel:DWORD src1_sel:WORD_1
	global_store_dwordx2 v[44:45], v[74:75], off offset:2048
	v_pk_mul_f32 v[74:75], v[42:43], v[72:73] op_sel_hi:[1,0]
	v_pk_mul_f32 v[72:73], v[60:61], v[72:73] op_sel_hi:[1,0]
	v_pk_mul_f32 v[74:75], v[12:13], v[74:75]
	v_pk_mul_f32 v[72:73], v[10:11], v[72:73]
	v_and_b32_sdwa v17, v75, v33 dst_sel:DWORD dst_unused:UNUSED_PAD src0_sel:WORD_1 src1_sel:DWORD
	v_and_b32_sdwa v76, v74, v33 dst_sel:DWORD dst_unused:UNUSED_PAD src0_sel:WORD_1 src1_sel:DWORD
	v_add3_u32 v74, v74, v76, s5
	v_add3_u32 v17, v75, v17, s5
	v_and_b32_sdwa v75, v73, v33 dst_sel:DWORD dst_unused:UNUSED_PAD src0_sel:WORD_1 src1_sel:DWORD
	v_and_b32_sdwa v76, v72, v33 dst_sel:DWORD dst_unused:UNUSED_PAD src0_sel:WORD_1 src1_sel:DWORD
	v_add3_u32 v73, v73, v75, s5
	v_add3_u32 v72, v72, v76, s5
	v_and_b32_e32 v73, 0xffff0000, v73
	v_and_b32_e32 v72, 0xffff0000, v72
	v_cmp_lt_i32_e32 vcc, s6, v16
	v_or_b32_sdwa v73, v73, v17 dst_sel:DWORD dst_unused:UNUSED_PAD src0_sel:DWORD src1_sel:WORD_1
	v_or_b32_sdwa v72, v72, v74 dst_sel:DWORD dst_unused:UNUSED_PAD src0_sel:DWORD src1_sel:WORD_1
	s_or_b64 s[2:3], vcc, s[2:3]
	global_store_dwordx2 v[44:45], v[72:73], off offset:3072
	s_andn2_b64 exec, exec, s[2:3]
	s_cbranch_execnz .LBB0_858
